# loop-edge rotation variant: moved block placed after the last MFMA, right before the loop-back barrier
# baseline (speedup 1.0000x reference)
; #define PG8_STAGE(bufoff, gbase, voff) do { _Pragma("unroll") for (int _i = 0; _i < 2; ++_i) \
;         __builtin_amdgcn_global_load_lds((const unsigned*)((const char*)(gbase) + (voff)[_i]), (PG8_LAS unsigned*)(lds + (bufoff) + ldsw + _i * 8192), 16, 0, 0); } while (0)
; #define PG8_LDA(dst, b, h) do { _Pragma("unroll") for (int m = 0; m < 4; ++m) _Pragma("unroll") for (int k = 0; k < 2; ++k) dst[m][k] = *(const PG8_LAS bf16x8*)(lds + PG8_SA(b, h) + aoff + m * 2048 + k * 1024); } while (0)
; #define PG8_LDB(dst, b, h) do { _Pragma("unroll") for (int n = 0; n < 2; ++n) _Pragma("unroll") for (int k = 0; k < 2; ++k) dst[n][k] = *(const PG8_LAS bf16x8*)(lds + PG8_SB(b, h) + boff + n * 2048 + k * 1024); } while (0)
; #define PG8_MMA(ai, bj, At, Bt) do { __builtin_amdgcn_s_setprio(1); _Pragma("unroll") for (int m = 0; m < 4; ++m) _Pragma("unroll") for (int n = 0; n < 2; ++n) _Pragma("unroll") for (int k = 0; k < 2; ++k) \
;         acc[ai][bj][m][n] = __builtin_amdgcn_mfma_f32_16x16x32_bf16(Bt[n][k], At[m][k], acc[ai][bj][m][n], 0, 0, 0); __builtin_amdgcn_s_setprio(0); } while (0)
; #define PG8_WAIT_V(n) asm volatile("s_waitcnt vmcnt(" #n ")" ::: "memory")
; #define PG8_WAIT_L(n) asm volatile("s_waitcnt lgkmcnt(" #n ")" ::: "memory")
; #define PG8_BAR __builtin_amdgcn_s_barrier()
; #define PG8_SCHED __builtin_amdgcn_sched_barrier(0)
; template <class Epi, class Sched, bool ALIGN_EPI = false, bool SP2 = false>
; __device__ __forceinline__ void gemm_phase(PG8_LAS unsigned char* lds, const Gemm g, const Sched& S, const Epi& E) {
;     ...
;             PG8_LDB(B0, 0, 0); PG8_LDB(B1, 0, 1); PG8_SCHED; PG8_LDA(At, 0, 0); PG8_STAGE(PG8_SA(1, 1), a1 + hstep, voffA);
;             PG8_WAIT_V(8); PG8_WAIT_L(0); PG8_BAR; PG8_MMA(0, 0, At, B0); PG8_MMA(0, 1, At, B1); PG8_BAR; PG8_SCHED;
;             PG8_LDA(At, 0, 1); PG8_STAGE(PG8_SB(0, 0), b2, voffB); PG8_STAGE(PG8_SB(0, 1), b2 + hstep, voffB); PG8_STAGE(PG8_SA(0, 0), a2, voffA);
;             PG8_WAIT_V(8); PG8_WAIT_L(0); PG8_BAR; PG8_MMA(1, 0, At, B0); PG8_MMA(1, 1, At, B1); PG8_BAR; PG8_SCHED;
.Lmy_rot2:
	s_add_i32 s15, 0, 0x14000
	ds_read_b128 v[146:149], v154
	ds_read_b128 v[150:153], v154 offset:1024
	ds_read_b128 v[162:165], v154 offset:2048
	ds_read_b128 v[166:169], v154 offset:3072
	v_add_u32_e32 v154, s15, v157
	ds_read_b128 v[170:173], v154
	ds_read_b128 v[174:177], v154 offset:1024
	ds_read_b128 v[178:181], v154 offset:2048
	ds_read_b128 v[186:189], v154 offset:3072
	v_lshl_add_u64 v[154:155], s[60:61], 0, v[144:145]
	s_add_i32 m0, s59, 0xc000
	ds_read_b128 v[190:193], v161
	ds_read_b128 v[194:197], v161 offset:1024
	ds_read_b128 v[198:201], v161 offset:2048
	ds_read_b128 v[202:205], v161 offset:3072
	ds_read_b128 v[208:211], v161 offset:4096
	ds_read_b128 v[212:215], v161 offset:5120
	ds_read_b128 v[216:219], v161 offset:6144
	ds_read_b128 v[220:223], v161 offset:7168
	global_load_lds_dwordx4 v[154:155], off
	v_lshl_add_u64 v[154:155], s[60:61], 0, v[140:141]
	s_add_i32 m0, s59, 0xe000
	s_nop 0
	global_load_lds_dwordx4 v[154:155], off
	s_waitcnt vmcnt(8)
	s_waitcnt lgkmcnt(0)
	s_barrier
	s_setprio 1
	s_waitcnt lgkmcnt(0)
	v_mfma_f32_16x16x32_bf16 v[130:133], v[146:149], v[190:193], v[130:133]
	v_mfma_f32_16x16x32_bf16 v[126:129], v[162:165], v[190:193], v[126:129]
	v_mfma_f32_16x16x32_bf16 v[114:117], v[146:149], v[198:201], v[114:117]
	v_mfma_f32_16x16x32_bf16 v[110:113], v[162:165], v[198:201], v[110:113]
	v_mfma_f32_16x16x32_bf16 v[94:97], v[146:149], v[208:211], v[94:97]
	v_mfma_f32_16x16x32_bf16 v[90:93], v[162:165], v[208:211], v[90:93]
	v_mfma_f32_16x16x32_bf16 v[78:81], v[146:149], v[216:219], v[78:81]
	v_mfma_f32_16x16x32_bf16 v[74:77], v[162:165], v[216:219], v[74:77]
	v_mfma_f32_16x16x32_bf16 v[130:133], v[150:153], v[194:197], v[130:133]
	v_mfma_f32_16x16x32_bf16 v[126:129], v[166:169], v[194:197], v[126:129]
	v_mfma_f32_16x16x32_bf16 v[114:117], v[150:153], v[202:205], v[114:117]
	v_mfma_f32_16x16x32_bf16 v[110:113], v[166:169], v[202:205], v[110:113]
	v_mfma_f32_16x16x32_bf16 v[94:97], v[150:153], v[212:215], v[94:97]
	v_mfma_f32_16x16x32_bf16 v[90:93], v[166:169], v[212:215], v[90:93]
	v_mfma_f32_16x16x32_bf16 v[78:81], v[150:153], v[220:223], v[78:81]
	v_mfma_f32_16x16x32_bf16 v[74:77], v[166:169], v[220:223], v[74:77]
	s_setprio 0
	s_setprio 1
	v_mfma_f32_16x16x32_bf16 v[122:125], v[170:173], v[190:193], v[122:125]
	v_mfma_f32_16x16x32_bf16 v[118:121], v[178:181], v[190:193], v[118:121]
	v_mfma_f32_16x16x32_bf16 v[106:109], v[170:173], v[198:201], v[106:109]
	v_mfma_f32_16x16x32_bf16 v[102:105], v[178:181], v[198:201], v[102:105]
	v_mfma_f32_16x16x32_bf16 v[86:89], v[170:173], v[208:211], v[86:89]
	v_mfma_f32_16x16x32_bf16 v[82:85], v[178:181], v[208:211], v[82:85]
	v_mfma_f32_16x16x32_bf16 v[70:73], v[170:173], v[216:219], v[70:73]
	v_mfma_f32_16x16x32_bf16 v[66:69], v[178:181], v[216:219], v[66:69]
	v_mfma_f32_16x16x32_bf16 v[122:125], v[174:177], v[194:197], v[122:125]
	v_mfma_f32_16x16x32_bf16 v[118:121], v[186:189], v[194:197], v[118:121]
	v_mfma_f32_16x16x32_bf16 v[106:109], v[174:177], v[202:205], v[106:109]
	v_mfma_f32_16x16x32_bf16 v[102:105], v[186:189], v[202:205], v[102:105]
	v_mfma_f32_16x16x32_bf16 v[86:89], v[174:177], v[212:215], v[86:89]
	v_mfma_f32_16x16x32_bf16 v[82:85], v[186:189], v[212:215], v[82:85]
	v_mfma_f32_16x16x32_bf16 v[70:73], v[174:177], v[220:223], v[70:73]
	v_mfma_f32_16x16x32_bf16 v[66:69], v[186:189], v[220:223], v[66:69]
	s_setprio 0
	s_barrier
	s_add_i32 s18, s25, s67
	v_lshl_add_u64 v[154:155], s[62:63], 0, v[0:1]
	s_mov_b32 m0, s18
	ds_read_b128 v[190:193], v161 offset:16384
	ds_read_b128 v[194:197], v161 offset:17408
	ds_read_b128 v[198:201], v161 offset:18432
	ds_read_b128 v[202:205], v161 offset:19456
	ds_read_b128 v[208:211], v161 offset:20480
	ds_read_b128 v[212:215], v161 offset:21504
	ds_read_b128 v[216:219], v161 offset:22528
	ds_read_b128 v[220:223], v161 offset:23552
	global_load_lds_dwordx4 v[154:155], off
	s_add_i32 m0, s18, 0x2000
	s_add_u32 s18, s62, 0x80000
	v_lshl_add_u64 v[182:183], s[62:63], 0, v[138:139]
	s_addc_u32 s19, s63, 0
	s_add_i32 s15, s15, s67
	global_load_lds_dwordx4 v[182:183], off
	v_lshl_add_u64 v[224:225], s[18:19], 0, v[0:1]
	s_mov_b32 m0, s15
	v_lshl_add_u64 v[226:227], s[64:65], 0, v[136:137]
	global_load_lds_dwordx4 v[224:225], off
	v_lshl_add_u64 v[224:225], s[18:19], 0, v[138:139]
	s_add_i32 m0, s15, 0x2000
	s_nop 0
	global_load_lds_dwordx4 v[224:225], off
	v_lshl_add_u64 v[224:225], s[64:65], 0, v[134:135]
	s_mov_b32 m0, s59
	s_nop 0
	global_load_lds_dwordx4 v[224:225], off
	s_mov_b32 m0, s68
	s_nop 0
	global_load_lds_dwordx4 v[226:227], off
	s_waitcnt vmcnt(8)
	s_waitcnt lgkmcnt(0)
	s_barrier
; #define PG8_STAGE(bufoff, gbase, voff) do { _Pragma("unroll") for (int _i = 0; _i < 2; ++_i) \
;         __builtin_amdgcn_global_load_lds((const unsigned*)((const char*)(gbase) + (voff)[_i]), (PG8_LAS unsigned*)(lds + (bufoff) + ldsw + _i * 8192), 16, 0, 0); } while (0)
; #define PG8_LDA(dst, b, h) do { _Pragma("unroll") for (int m = 0; m < 4; ++m) _Pragma("unroll") for (int k = 0; k < 2; ++k) dst[m][k] = *(const PG8_LAS bf16x8*)(lds + PG8_SA(b, h) + aoff + m * 2048 + k * 1024); } while (0)
; #define PG8_LDB(dst, b, h) do { _Pragma("unroll") for (int n = 0; n < 2; ++n) _Pragma("unroll") for (int k = 0; k < 2; ++k) dst[n][k] = *(const PG8_LAS bf16x8*)(lds + PG8_SB(b, h) + boff + n * 2048 + k * 1024); } while (0)
; #define PG8_MMA(ai, bj, At, Bt) do { __builtin_amdgcn_s_setprio(1); _Pragma("unroll") for (int m = 0; m < 4; ++m) _Pragma("unroll") for (int n = 0; n < 2; ++n) _Pragma("unroll") for (int k = 0; k < 2; ++k) \
;         acc[ai][bj][m][n] = __builtin_amdgcn_mfma_f32_16x16x32_bf16(Bt[n][k], At[m][k], acc[ai][bj][m][n], 0, 0, 0); __builtin_amdgcn_s_setprio(0); } while (0)
; #define PG8_WAIT_V(n) asm volatile("s_waitcnt vmcnt(" #n ")" ::: "memory")
; #define PG8_WAIT_L(n) asm volatile("s_waitcnt lgkmcnt(" #n ")" ::: "memory")
; #define PG8_BAR __builtin_amdgcn_s_barrier()
; #define PG8_SCHED __builtin_amdgcn_sched_barrier(0)
; template <class Epi, class Sched, bool ALIGN_EPI = false, bool SP2 = false>
; __device__ __forceinline__ void gemm_phase(PG8_LAS unsigned char* lds, const Gemm g, const Sched& S, const Epi& E) {
;     ...
;             PG8_WAIT_V(8); PG8_WAIT_L(0); PG8_BAR; PG8_MMA(1, 0, At, B0); PG8_MMA(1, 1, At, B1); PG8_BAR; PG8_SCHED;
;             PG8_LDB(B0, 1, 0); PG8_LDB(B1, 1, 1); PG8_SCHED; PG8_LDA(At, 1, 0); PG8_STAGE(PG8_SA(0, 1), a2 + hstep, voffA);
;             PG8_WAIT_V(8); PG8_WAIT_L(0); PG8_BAR; PG8_MMA(0, 0, At, B0); PG8_MMA(0, 1, At, B1); PG8_BAR; PG8_SCHED;
	s_setprio 1
	s_waitcnt lgkmcnt(0)
	v_mfma_f32_16x16x32_bf16 v[62:65], v[146:149], v[190:193], v[62:65]
	v_mfma_f32_16x16x32_bf16 v[58:61], v[162:165], v[190:193], v[58:61]
	v_mfma_f32_16x16x32_bf16 v[46:49], v[146:149], v[198:201], v[46:49]
	v_mfma_f32_16x16x32_bf16 v[42:45], v[162:165], v[198:201], v[42:45]
	v_mfma_f32_16x16x32_bf16 v[30:33], v[146:149], v[208:211], v[30:33]
	v_mfma_f32_16x16x32_bf16 v[26:29], v[162:165], v[208:211], v[26:29]
	v_mfma_f32_16x16x32_bf16 v[14:17], v[146:149], v[216:219], v[14:17]
	v_mfma_f32_16x16x32_bf16 v[10:13], v[162:165], v[216:219], v[10:13]
	v_mfma_f32_16x16x32_bf16 v[62:65], v[150:153], v[194:197], v[62:65]
	v_mfma_f32_16x16x32_bf16 v[58:61], v[166:169], v[194:197], v[58:61]
	v_mfma_f32_16x16x32_bf16 v[46:49], v[150:153], v[202:205], v[46:49]
	v_mfma_f32_16x16x32_bf16 v[42:45], v[166:169], v[202:205], v[42:45]
	v_mfma_f32_16x16x32_bf16 v[30:33], v[150:153], v[212:215], v[30:33]
	v_mfma_f32_16x16x32_bf16 v[26:29], v[166:169], v[212:215], v[26:29]
	v_mfma_f32_16x16x32_bf16 v[14:17], v[150:153], v[220:223], v[14:17]
	v_mfma_f32_16x16x32_bf16 v[10:13], v[166:169], v[220:223], v[10:13]
	s_setprio 0
	s_setprio 1
	v_mfma_f32_16x16x32_bf16 v[54:57], v[170:173], v[190:193], v[54:57]
	v_mfma_f32_16x16x32_bf16 v[50:53], v[178:181], v[190:193], v[50:53]
	v_mfma_f32_16x16x32_bf16 v[38:41], v[170:173], v[198:201], v[38:41]
	v_mfma_f32_16x16x32_bf16 v[34:37], v[178:181], v[198:201], v[34:37]
	v_mfma_f32_16x16x32_bf16 v[22:25], v[170:173], v[208:211], v[22:25]
	v_mfma_f32_16x16x32_bf16 v[18:21], v[178:181], v[208:211], v[18:21]
	v_mfma_f32_16x16x32_bf16 v[6:9], v[170:173], v[216:219], v[6:9]
	v_mfma_f32_16x16x32_bf16 v[2:5], v[178:181], v[216:219], v[2:5]
	v_mfma_f32_16x16x32_bf16 v[54:57], v[174:177], v[194:197], v[54:57]
	v_mfma_f32_16x16x32_bf16 v[50:53], v[186:189], v[194:197], v[50:53]
	v_mfma_f32_16x16x32_bf16 v[38:41], v[174:177], v[202:205], v[38:41]
	v_mfma_f32_16x16x32_bf16 v[34:37], v[186:189], v[202:205], v[34:37]
	v_mfma_f32_16x16x32_bf16 v[22:25], v[174:177], v[212:215], v[22:25]
	v_mfma_f32_16x16x32_bf16 v[18:21], v[186:189], v[212:215], v[18:21]
	v_mfma_f32_16x16x32_bf16 v[6:9], v[174:177], v[220:223], v[6:9]
	v_mfma_f32_16x16x32_bf16 v[2:5], v[186:189], v[220:223], v[2:5]
	s_setprio 0
	s_barrier
	s_add_i32 s15, 0, 0x18000
	s_add_i32 s25, 0, 0x1c000
	v_add_u32_e32 v166, s15, v157
	v_add_u32_e32 v184, s25, v157
	ds_read_b128 v[146:149], v166
	ds_read_b128 v[150:153], v166 offset:1024
	ds_read_b128 v[162:165], v166 offset:2048
	ds_read_b128 v[166:169], v166 offset:3072
	ds_read_b128 v[170:173], v184
	ds_read_b128 v[174:177], v184 offset:1024
	ds_read_b128 v[178:181], v184 offset:2048
	ds_read_b128 v[186:189], v184 offset:3072
	s_add_u32 s18, s64, 0x80000
	s_addc_u32 s19, s65, 0
	s_mov_b32 m0, s69
	v_lshl_add_u64 v[230:231], s[18:19], 0, v[134:135]
	ds_read_b128 v[190:193], v161 offset:32768
	ds_read_b128 v[194:197], v161 offset:33792
	ds_read_b128 v[198:201], v161 offset:34816
	ds_read_b128 v[202:205], v161 offset:35840
	ds_read_b128 v[208:211], v161 offset:36864
	ds_read_b128 v[212:215], v161 offset:37888
	ds_read_b128 v[216:219], v161 offset:38912
	ds_read_b128 v[220:223], v161 offset:39936
	global_load_lds_dwordx4 v[230:231], off
	v_lshl_add_u64 v[230:231], s[18:19], 0, v[136:137]
	s_mov_b32 m0, s70
	s_nop 0
	global_load_lds_dwordx4 v[230:231], off
	s_waitcnt vmcnt(8)
	s_waitcnt lgkmcnt(0)
	s_barrier
	s_setprio 1
	s_waitcnt lgkmcnt(0)
	v_mfma_f32_16x16x32_bf16 v[130:133], v[146:149], v[190:193], v[130:133]
	v_mfma_f32_16x16x32_bf16 v[126:129], v[162:165], v[190:193], v[126:129]
	v_mfma_f32_16x16x32_bf16 v[114:117], v[146:149], v[198:201], v[114:117]
	v_mfma_f32_16x16x32_bf16 v[110:113], v[162:165], v[198:201], v[110:113]
	v_mfma_f32_16x16x32_bf16 v[94:97], v[146:149], v[208:211], v[94:97]
	v_mfma_f32_16x16x32_bf16 v[90:93], v[162:165], v[208:211], v[90:93]
	v_mfma_f32_16x16x32_bf16 v[78:81], v[146:149], v[216:219], v[78:81]
	v_mfma_f32_16x16x32_bf16 v[74:77], v[162:165], v[216:219], v[74:77]
	v_mfma_f32_16x16x32_bf16 v[130:133], v[150:153], v[194:197], v[130:133]
	v_mfma_f32_16x16x32_bf16 v[126:129], v[166:169], v[194:197], v[126:129]
	v_mfma_f32_16x16x32_bf16 v[114:117], v[150:153], v[202:205], v[114:117]
	v_mfma_f32_16x16x32_bf16 v[110:113], v[166:169], v[202:205], v[110:113]
	v_mfma_f32_16x16x32_bf16 v[94:97], v[150:153], v[212:215], v[94:97]
	v_mfma_f32_16x16x32_bf16 v[90:93], v[166:169], v[212:215], v[90:93]
	v_mfma_f32_16x16x32_bf16 v[78:81], v[150:153], v[220:223], v[78:81]
	v_mfma_f32_16x16x32_bf16 v[74:77], v[166:169], v[220:223], v[74:77]
	s_setprio 0
	s_setprio 1
	v_mfma_f32_16x16x32_bf16 v[122:125], v[170:173], v[190:193], v[122:125]
	v_mfma_f32_16x16x32_bf16 v[118:121], v[178:181], v[190:193], v[118:121]
	v_mfma_f32_16x16x32_bf16 v[106:109], v[170:173], v[198:201], v[106:109]
	v_mfma_f32_16x16x32_bf16 v[102:105], v[178:181], v[198:201], v[102:105]
	v_mfma_f32_16x16x32_bf16 v[86:89], v[170:173], v[208:211], v[86:89]
	v_mfma_f32_16x16x32_bf16 v[82:85], v[178:181], v[208:211], v[82:85]
	v_mfma_f32_16x16x32_bf16 v[70:73], v[170:173], v[216:219], v[70:73]
	v_mfma_f32_16x16x32_bf16 v[66:69], v[178:181], v[216:219], v[66:69]
	v_mfma_f32_16x16x32_bf16 v[122:125], v[174:177], v[194:197], v[122:125]
	v_mfma_f32_16x16x32_bf16 v[118:121], v[186:189], v[194:197], v[118:121]
	v_mfma_f32_16x16x32_bf16 v[106:109], v[174:177], v[202:205], v[106:109]
	v_mfma_f32_16x16x32_bf16 v[102:105], v[186:189], v[202:205], v[102:105]
	v_mfma_f32_16x16x32_bf16 v[86:89], v[174:177], v[212:215], v[86:89]
	v_mfma_f32_16x16x32_bf16 v[82:85], v[186:189], v[212:215], v[82:85]
	v_mfma_f32_16x16x32_bf16 v[70:73], v[174:177], v[220:223], v[70:73]
	v_mfma_f32_16x16x32_bf16 v[66:69], v[186:189], v[220:223], v[66:69]
	s_setprio 0
	s_barrier
; #define PG8_STAGE(bufoff, gbase, voff) do { _Pragma("unroll") for (int _i = 0; _i < 2; ++_i) \
;         __builtin_amdgcn_global_load_lds((const unsigned*)((const char*)(gbase) + (voff)[_i]), (PG8_LAS unsigned*)(lds + (bufoff) + ldsw + _i * 8192), 16, 0, 0); } while (0)
; #define PG8_LDA(dst, b, h) do { _Pragma("unroll") for (int m = 0; m < 4; ++m) _Pragma("unroll") for (int k = 0; k < 2; ++k) dst[m][k] = *(const PG8_LAS bf16x8*)(lds + PG8_SA(b, h) + aoff + m * 2048 + k * 1024); } while (0)
; #define PG8_MMA(ai, bj, At, Bt) do { __builtin_amdgcn_s_setprio(1); _Pragma("unroll") for (int m = 0; m < 4; ++m) _Pragma("unroll") for (int n = 0; n < 2; ++n) _Pragma("unroll") for (int k = 0; k < 2; ++k) \
;         acc[ai][bj][m][n] = __builtin_amdgcn_mfma_f32_16x16x32_bf16(Bt[n][k], At[m][k], acc[ai][bj][m][n], 0, 0, 0); __builtin_amdgcn_s_setprio(0); } while (0)
; #define PG8_WAIT_V(n) asm volatile("s_waitcnt vmcnt(" #n ")" ::: "memory")
; #define PG8_WAIT_L(n) asm volatile("s_waitcnt lgkmcnt(" #n ")" ::: "memory")
; #define PG8_BAR __builtin_amdgcn_s_barrier()
; #define PG8_SCHED __builtin_amdgcn_sched_barrier(0)
; template <class Epi, class Sched, bool ALIGN_EPI = false, bool SP2 = false>
; __device__ __forceinline__ void gemm_phase(PG8_LAS unsigned char* lds, const Gemm g, const Sched& S, const Epi& E) {
;     ...
;         for (int t = 0; t < nt; t += 2) {
;             const bool last = (t == nt - 2);
;             const char* a1 = cA + (size_t)(t + 1) * kstep;
;             const char* a2 = last ? nA : cA + (size_t)(t + 2) * kstep; const char* b2 = last ? nB : cB + (size_t)(t + 2) * kstep;
;             const char* a3 = a2 + kstep; const char* b3 = b2 + kstep;
;     ...
;             PG8_LDA(At, 1, 1); PG8_STAGE(PG8_SB(1, 0), b3, voffB); PG8_STAGE(PG8_SB(1, 1), b3 + hstep, voffB); PG8_STAGE(PG8_SA(1, 0), a3, voffA);
;             PG8_WAIT_V(8); PG8_WAIT_L(0); PG8_BAR; PG8_MMA(1, 0, At, B0); PG8_MMA(1, 1, At, B1); PG8_BAR; PG8_SCHED;
	s_add_i32 s15, s15, s67
	v_lshl_add_u64 v[154:155], v[154:155], 0, s[22:23]
	s_mov_b32 m0, s15
	ds_read_b128 v[190:193], v161 offset:49152
	ds_read_b128 v[194:197], v161 offset:50176
	ds_read_b128 v[198:201], v161 offset:51200
	ds_read_b128 v[202:205], v161 offset:52224
	ds_read_b128 v[208:211], v161 offset:53248
	ds_read_b128 v[212:215], v161 offset:54272
	ds_read_b128 v[216:219], v161 offset:55296
	ds_read_b128 v[220:223], v161 offset:56320
	global_load_lds_dwordx4 v[154:155], off
	s_add_i32 m0, s15, 0x2000
	s_add_u32 s18, s62, 0x80080
	v_lshl_add_u64 v[154:155], v[182:183], 0, s[22:23]
	s_addc_u32 s19, s63, 0
	s_add_i32 s15, s25, s67
	global_load_lds_dwordx4 v[154:155], off
	v_lshl_add_u64 v[154:155], s[18:19], 0, v[0:1]
	s_mov_b32 m0, s15
	s_nop 0
	global_load_lds_dwordx4 v[154:155], off
	v_lshl_add_u64 v[154:155], s[18:19], 0, v[138:139]
	s_add_i32 m0, s15, 0x2000
	s_nop 0
	global_load_lds_dwordx4 v[154:155], off
	v_lshl_add_u64 v[154:155], v[224:225], 0, s[22:23]
	s_mov_b32 m0, s75
	s_nop 0
	global_load_lds_dwordx4 v[154:155], off
	v_lshl_add_u64 v[154:155], v[226:227], 0, s[22:23]
	s_mov_b32 m0, s76
	s_nop 0
	global_load_lds_dwordx4 v[154:155], off
	s_waitcnt vmcnt(8)
	s_waitcnt lgkmcnt(0)
	s_barrier
	s_setprio 1
	s_waitcnt lgkmcnt(0)
	v_mfma_f32_16x16x32_bf16 v[62:65], v[146:149], v[190:193], v[62:65]
	v_mfma_f32_16x16x32_bf16 v[58:61], v[162:165], v[190:193], v[58:61]
	v_mfma_f32_16x16x32_bf16 v[46:49], v[146:149], v[198:201], v[46:49]
	v_mfma_f32_16x16x32_bf16 v[42:45], v[162:165], v[198:201], v[42:45]
	v_mfma_f32_16x16x32_bf16 v[30:33], v[146:149], v[208:211], v[30:33]
	v_mfma_f32_16x16x32_bf16 v[26:29], v[162:165], v[208:211], v[26:29]
	v_mfma_f32_16x16x32_bf16 v[14:17], v[146:149], v[216:219], v[14:17]
	v_mfma_f32_16x16x32_bf16 v[10:13], v[162:165], v[216:219], v[10:13]
	v_mfma_f32_16x16x32_bf16 v[62:65], v[150:153], v[194:197], v[62:65]
	v_mfma_f32_16x16x32_bf16 v[58:61], v[166:169], v[194:197], v[58:61]
	v_mfma_f32_16x16x32_bf16 v[46:49], v[150:153], v[202:205], v[46:49]
	v_mfma_f32_16x16x32_bf16 v[42:45], v[166:169], v[202:205], v[42:45]
	v_mfma_f32_16x16x32_bf16 v[30:33], v[150:153], v[212:215], v[30:33]
	v_mfma_f32_16x16x32_bf16 v[26:29], v[166:169], v[212:215], v[26:29]
	v_mfma_f32_16x16x32_bf16 v[14:17], v[150:153], v[220:223], v[14:17]
	v_mfma_f32_16x16x32_bf16 v[10:13], v[166:169], v[220:223], v[10:13]
	s_setprio 0
	s_setprio 1
	v_mfma_f32_16x16x32_bf16 v[54:57], v[170:173], v[190:193], v[54:57]
	v_mfma_f32_16x16x32_bf16 v[50:53], v[178:181], v[190:193], v[50:53]
	v_mfma_f32_16x16x32_bf16 v[38:41], v[170:173], v[198:201], v[38:41]
	v_mfma_f32_16x16x32_bf16 v[34:37], v[178:181], v[198:201], v[34:37]
	v_mfma_f32_16x16x32_bf16 v[22:25], v[170:173], v[208:211], v[22:25]
	v_mfma_f32_16x16x32_bf16 v[18:21], v[178:181], v[208:211], v[18:21]
	v_mfma_f32_16x16x32_bf16 v[6:9], v[170:173], v[216:219], v[6:9]
	v_mfma_f32_16x16x32_bf16 v[2:5], v[178:181], v[216:219], v[2:5]
	v_mfma_f32_16x16x32_bf16 v[54:57], v[174:177], v[194:197], v[54:57]
	v_mfma_f32_16x16x32_bf16 v[50:53], v[186:189], v[194:197], v[50:53]
	v_mfma_f32_16x16x32_bf16 v[38:41], v[174:177], v[202:205], v[38:41]
	v_mfma_f32_16x16x32_bf16 v[34:37], v[186:189], v[202:205], v[34:37]
	v_mfma_f32_16x16x32_bf16 v[22:25], v[174:177], v[212:215], v[22:25]
	v_mfma_f32_16x16x32_bf16 v[18:21], v[186:189], v[212:215], v[18:21]
	v_mfma_f32_16x16x32_bf16 v[6:9], v[174:177], v[220:223], v[6:9]
	v_mfma_f32_16x16x32_bf16 v[2:5], v[186:189], v[220:223], v[2:5]
	s_add_u32 s12, s12, 0x100
	s_addc_u32 s14, s14, 0
	s_add_u32 s60, s60, 0x100
	s_addc_u32 s61, s61, 0
	s_mov_b32 s15, s16
	s_add_i32 s16, s15, 2
	s_add_u32 s18, s60, 0xfff80080
	s_addc_u32 s19, s61, -1
	s_add_i32 s25, 0, 0x10000
	s_cmp_eq_u32 s77, s15
	s_cselect_b32 s65, s2, s19
	s_cselect_b32 s64, s3, s18
	v_add_u32_e32 v154, s25, v157
	s_cselect_b32 s63, s8, s14
	s_cselect_b32 s62, s9, s12
	s_cmp_ge_u32 s15, s74
	s_setprio 0
	s_barrier
	s_cbranch_scc0 .Lmy_rot2
	s_and_b64 vcc, exec, s[46:47]
	s_cbranch_vccz .LBB0_1204
	s_barrier

; #define PG8_STAGE(bufoff, gbase, voff) do { _Pragma("unroll") for (int _i = 0; _i < 2; ++_i) \
;         __builtin_amdgcn_global_load_lds((const unsigned*)((const char*)(gbase) + (voff)[_i]), (PG8_LAS unsigned*)(lds + (bufoff) + ldsw + _i * 8192), 16, 0, 0); } while (0)
; #define PG8_LDA(dst, b, h) do { _Pragma("unroll") for (int m = 0; m < 4; ++m) _Pragma("unroll") for (int k = 0; k < 2; ++k) dst[m][k] = *(const PG8_LAS bf16x8*)(lds + PG8_SA(b, h) + aoff + m * 2048 + k * 1024); } while (0)
; #define PG8_LDB(dst, b, h) do { _Pragma("unroll") for (int n = 0; n < 2; ++n) _Pragma("unroll") for (int k = 0; k < 2; ++k) dst[n][k] = *(const PG8_LAS bf16x8*)(lds + PG8_SB(b, h) + boff + n * 2048 + k * 1024); } while (0)
; #define PG8_MMA(ai, bj, At, Bt) do { __builtin_amdgcn_s_setprio(1); _Pragma("unroll") for (int m = 0; m < 4; ++m) _Pragma("unroll") for (int n = 0; n < 2; ++n) _Pragma("unroll") for (int k = 0; k < 2; ++k) \
;         acc[ai][bj][m][n] = __builtin_amdgcn_mfma_f32_16x16x32_bf16(Bt[n][k], At[m][k], acc[ai][bj][m][n], 0, 0, 0); __builtin_amdgcn_s_setprio(0); } while (0)
; #define PG8_WAIT_V(n) asm volatile("s_waitcnt vmcnt(" #n ")" ::: "memory")
; #define PG8_WAIT_L(n) asm volatile("s_waitcnt lgkmcnt(" #n ")" ::: "memory")
; #define PG8_BAR __builtin_amdgcn_s_barrier()
; #define PG8_SCHED __builtin_amdgcn_sched_barrier(0)
; template <class Epi, class Sched, bool ALIGN_EPI = false, bool SP2 = false>
; __device__ __forceinline__ void gemm_phase(PG8_LAS unsigned char* lds, const Gemm g, const Sched& S, const Epi& E) {
;     ...
;             PG8_LDB(B0, 0, 0); PG8_LDB(B1, 0, 1); PG8_SCHED; PG8_LDA(At, 0, 0); PG8_STAGE(PG8_SA(1, 1), a1 + hstep, voffA);
;             PG8_WAIT_V(8); PG8_WAIT_L(0); PG8_BAR; PG8_MMA(0, 0, At, B0); PG8_MMA(0, 1, At, B1); PG8_BAR; PG8_SCHED;
;             PG8_LDA(At, 0, 1); PG8_STAGE(PG8_SB(0, 0), b2, voffB); PG8_STAGE(PG8_SB(0, 1), b2 + hstep, voffB); PG8_STAGE(PG8_SA(0, 0), a2, voffA);
;             PG8_WAIT_V(8); PG8_WAIT_L(0); PG8_BAR; PG8_MMA(1, 0, At, B0); PG8_MMA(1, 1, At, B1); PG8_BAR; PG8_SCHED;
.Lmy_rot1:
	s_add_i32 s41, 0, 0x14000
	ds_read_b128 v[146:149], v154
	ds_read_b128 v[150:153], v154 offset:1024
	ds_read_b128 v[160:163], v154 offset:2048
	ds_read_b128 v[164:167], v154 offset:3072
	v_add_u32_e32 v154, s41, v157
	ds_read_b128 v[168:171], v154
	ds_read_b128 v[172:175], v154 offset:1024
	ds_read_b128 v[176:179], v154 offset:2048
	ds_read_b128 v[180:183], v154 offset:3072
	v_lshl_add_u64 v[154:155], s[0:1], 0, v[144:145]
	s_add_i32 m0, s16, 0xc000
	ds_read_b128 v[186:189], v159
	ds_read_b128 v[190:193], v159 offset:1024
	ds_read_b128 v[194:197], v159 offset:2048
	ds_read_b128 v[198:201], v159 offset:3072
	ds_read_b128 v[202:205], v159 offset:4096
	ds_read_b128 v[208:211], v159 offset:5120
	ds_read_b128 v[212:215], v159 offset:6144
	ds_read_b128 v[216:219], v159 offset:7168
	global_load_lds_dwordx4 v[154:155], off
	v_lshl_add_u64 v[154:155], s[0:1], 0, v[140:141]
	s_add_i32 m0, s16, 0xe000
	s_nop 0
	global_load_lds_dwordx4 v[154:155], off
	s_waitcnt vmcnt(8)
	s_waitcnt lgkmcnt(0)
	s_barrier
	s_setprio 1
	s_waitcnt lgkmcnt(0)
	v_mfma_f32_16x16x32_bf16 v[130:133], v[146:149], v[186:189], v[130:133]
	v_mfma_f32_16x16x32_bf16 v[126:129], v[160:163], v[186:189], v[126:129]
	v_mfma_f32_16x16x32_bf16 v[114:117], v[146:149], v[194:197], v[114:117]
	v_mfma_f32_16x16x32_bf16 v[110:113], v[160:163], v[194:197], v[110:113]
	v_mfma_f32_16x16x32_bf16 v[94:97], v[146:149], v[202:205], v[94:97]
	v_mfma_f32_16x16x32_bf16 v[90:93], v[160:163], v[202:205], v[90:93]
	v_mfma_f32_16x16x32_bf16 v[78:81], v[146:149], v[212:215], v[78:81]
	v_mfma_f32_16x16x32_bf16 v[74:77], v[160:163], v[212:215], v[74:77]
	v_mfma_f32_16x16x32_bf16 v[130:133], v[150:153], v[190:193], v[130:133]
	v_mfma_f32_16x16x32_bf16 v[126:129], v[164:167], v[190:193], v[126:129]
	v_mfma_f32_16x16x32_bf16 v[114:117], v[150:153], v[198:201], v[114:117]
	v_mfma_f32_16x16x32_bf16 v[110:113], v[164:167], v[198:201], v[110:113]
	v_mfma_f32_16x16x32_bf16 v[94:97], v[150:153], v[208:211], v[94:97]
	v_mfma_f32_16x16x32_bf16 v[90:93], v[164:167], v[208:211], v[90:93]
	v_mfma_f32_16x16x32_bf16 v[78:81], v[150:153], v[216:219], v[78:81]
	v_mfma_f32_16x16x32_bf16 v[74:77], v[164:167], v[216:219], v[74:77]
	s_setprio 0
	s_setprio 1
	v_mfma_f32_16x16x32_bf16 v[122:125], v[168:171], v[186:189], v[122:125]
	v_mfma_f32_16x16x32_bf16 v[118:121], v[176:179], v[186:189], v[118:121]
	v_mfma_f32_16x16x32_bf16 v[106:109], v[168:171], v[194:197], v[106:109]
	v_mfma_f32_16x16x32_bf16 v[102:105], v[176:179], v[194:197], v[102:105]
	v_mfma_f32_16x16x32_bf16 v[86:89], v[168:171], v[202:205], v[86:89]
	v_mfma_f32_16x16x32_bf16 v[82:85], v[176:179], v[202:205], v[82:85]
	v_mfma_f32_16x16x32_bf16 v[70:73], v[168:171], v[212:215], v[70:73]
	v_mfma_f32_16x16x32_bf16 v[66:69], v[176:179], v[212:215], v[66:69]
	v_mfma_f32_16x16x32_bf16 v[122:125], v[172:175], v[190:193], v[122:125]
	v_mfma_f32_16x16x32_bf16 v[118:121], v[180:183], v[190:193], v[118:121]
	v_mfma_f32_16x16x32_bf16 v[106:109], v[172:175], v[198:201], v[106:109]
	v_mfma_f32_16x16x32_bf16 v[102:105], v[180:183], v[198:201], v[102:105]
	v_mfma_f32_16x16x32_bf16 v[86:89], v[172:175], v[208:211], v[86:89]
	v_mfma_f32_16x16x32_bf16 v[82:85], v[180:183], v[208:211], v[82:85]
	v_mfma_f32_16x16x32_bf16 v[70:73], v[172:175], v[216:219], v[70:73]
	v_mfma_f32_16x16x32_bf16 v[66:69], v[180:183], v[216:219], v[66:69]
	s_setprio 0
	s_barrier
	s_add_i32 s51, s51, s10
	v_lshl_add_u64 v[154:155], s[42:43], 0, v[0:1]
	s_mov_b32 m0, s51
	ds_read_b128 v[186:189], v159 offset:16384
	ds_read_b128 v[190:193], v159 offset:17408
	ds_read_b128 v[194:197], v159 offset:18432
	ds_read_b128 v[198:201], v159 offset:19456
	ds_read_b128 v[202:205], v159 offset:20480
	ds_read_b128 v[208:211], v159 offset:21504
	ds_read_b128 v[212:215], v159 offset:22528
	ds_read_b128 v[216:219], v159 offset:23552
	global_load_lds_dwordx4 v[154:155], off
	s_add_i32 m0, s51, 0x2000
	s_add_u32 s60, s42, 0x80000
	v_lshl_add_u64 v[220:221], s[42:43], 0, v[138:139]
	s_addc_u32 s61, s43, 0
	s_add_i32 s41, s41, s10
	global_load_lds_dwordx4 v[220:221], off
	v_lshl_add_u64 v[222:223], s[60:61], 0, v[0:1]
	s_mov_b32 m0, s41
	v_lshl_add_u64 v[224:225], s[58:59], 0, v[136:137]
	global_load_lds_dwordx4 v[222:223], off
	v_lshl_add_u64 v[222:223], s[60:61], 0, v[138:139]
	s_add_i32 m0, s41, 0x2000
	s_nop 0
	global_load_lds_dwordx4 v[222:223], off
	v_lshl_add_u64 v[222:223], s[58:59], 0, v[134:135]
	s_mov_b32 m0, s16
	s_nop 0
	global_load_lds_dwordx4 v[222:223], off
	s_mov_b32 m0, s17
	s_nop 0
	global_load_lds_dwordx4 v[224:225], off
	s_waitcnt vmcnt(8)
	s_waitcnt lgkmcnt(0)
	s_barrier
; #define PG8_STAGE(bufoff, gbase, voff) do { _Pragma("unroll") for (int _i = 0; _i < 2; ++_i) \
;         __builtin_amdgcn_global_load_lds((const unsigned*)((const char*)(gbase) + (voff)[_i]), (PG8_LAS unsigned*)(lds + (bufoff) + ldsw + _i * 8192), 16, 0, 0); } while (0)
; #define PG8_LDA(dst, b, h) do { _Pragma("unroll") for (int m = 0; m < 4; ++m) _Pragma("unroll") for (int k = 0; k < 2; ++k) dst[m][k] = *(const PG8_LAS bf16x8*)(lds + PG8_SA(b, h) + aoff + m * 2048 + k * 1024); } while (0)
; #define PG8_LDB(dst, b, h) do { _Pragma("unroll") for (int n = 0; n < 2; ++n) _Pragma("unroll") for (int k = 0; k < 2; ++k) dst[n][k] = *(const PG8_LAS bf16x8*)(lds + PG8_SB(b, h) + boff + n * 2048 + k * 1024); } while (0)
; #define PG8_MMA(ai, bj, At, Bt) do { __builtin_amdgcn_s_setprio(1); _Pragma("unroll") for (int m = 0; m < 4; ++m) _Pragma("unroll") for (int n = 0; n < 2; ++n) _Pragma("unroll") for (int k = 0; k < 2; ++k) \
;         acc[ai][bj][m][n] = __builtin_amdgcn_mfma_f32_16x16x32_bf16(Bt[n][k], At[m][k], acc[ai][bj][m][n], 0, 0, 0); __builtin_amdgcn_s_setprio(0); } while (0)
; #define PG8_WAIT_V(n) asm volatile("s_waitcnt vmcnt(" #n ")" ::: "memory")
; #define PG8_WAIT_L(n) asm volatile("s_waitcnt lgkmcnt(" #n ")" ::: "memory")
; #define PG8_BAR __builtin_amdgcn_s_barrier()
; #define PG8_SCHED __builtin_amdgcn_sched_barrier(0)
; template <class Epi, class Sched, bool ALIGN_EPI = false, bool SP2 = false>
; __device__ __forceinline__ void gemm_phase(PG8_LAS unsigned char* lds, const Gemm g, const Sched& S, const Epi& E) {
;     ...
;             PG8_WAIT_V(8); PG8_WAIT_L(0); PG8_BAR; PG8_MMA(1, 0, At, B0); PG8_MMA(1, 1, At, B1); PG8_BAR; PG8_SCHED;
;             PG8_LDB(B0, 1, 0); PG8_LDB(B1, 1, 1); PG8_SCHED; PG8_LDA(At, 1, 0); PG8_STAGE(PG8_SA(0, 1), a2 + hstep, voffA);
;             PG8_WAIT_V(8); PG8_WAIT_L(0); PG8_BAR; PG8_MMA(0, 0, At, B0); PG8_MMA(0, 1, At, B1); PG8_BAR; PG8_SCHED;
	s_setprio 1
	s_waitcnt lgkmcnt(0)
	v_mfma_f32_16x16x32_bf16 v[62:65], v[146:149], v[186:189], v[62:65]
	v_mfma_f32_16x16x32_bf16 v[58:61], v[160:163], v[186:189], v[58:61]
	v_mfma_f32_16x16x32_bf16 v[46:49], v[146:149], v[194:197], v[46:49]
	v_mfma_f32_16x16x32_bf16 v[42:45], v[160:163], v[194:197], v[42:45]
	v_mfma_f32_16x16x32_bf16 v[30:33], v[146:149], v[202:205], v[30:33]
	v_mfma_f32_16x16x32_bf16 v[26:29], v[160:163], v[202:205], v[26:29]
	v_mfma_f32_16x16x32_bf16 v[14:17], v[146:149], v[212:215], v[14:17]
	v_mfma_f32_16x16x32_bf16 v[10:13], v[160:163], v[212:215], v[10:13]
	v_mfma_f32_16x16x32_bf16 v[62:65], v[150:153], v[190:193], v[62:65]
	v_mfma_f32_16x16x32_bf16 v[58:61], v[164:167], v[190:193], v[58:61]
	v_mfma_f32_16x16x32_bf16 v[46:49], v[150:153], v[198:201], v[46:49]
	v_mfma_f32_16x16x32_bf16 v[42:45], v[164:167], v[198:201], v[42:45]
	v_mfma_f32_16x16x32_bf16 v[30:33], v[150:153], v[208:211], v[30:33]
	v_mfma_f32_16x16x32_bf16 v[26:29], v[164:167], v[208:211], v[26:29]
	v_mfma_f32_16x16x32_bf16 v[14:17], v[150:153], v[216:219], v[14:17]
	v_mfma_f32_16x16x32_bf16 v[10:13], v[164:167], v[216:219], v[10:13]
	s_setprio 0
	s_setprio 1
	v_mfma_f32_16x16x32_bf16 v[54:57], v[168:171], v[186:189], v[54:57]
	v_mfma_f32_16x16x32_bf16 v[50:53], v[176:179], v[186:189], v[50:53]
	v_mfma_f32_16x16x32_bf16 v[38:41], v[168:171], v[194:197], v[38:41]
	v_mfma_f32_16x16x32_bf16 v[34:37], v[176:179], v[194:197], v[34:37]
	v_mfma_f32_16x16x32_bf16 v[22:25], v[168:171], v[202:205], v[22:25]
	v_mfma_f32_16x16x32_bf16 v[18:21], v[176:179], v[202:205], v[18:21]
	v_mfma_f32_16x16x32_bf16 v[6:9], v[168:171], v[212:215], v[6:9]
	v_mfma_f32_16x16x32_bf16 v[2:5], v[176:179], v[212:215], v[2:5]
	v_mfma_f32_16x16x32_bf16 v[54:57], v[172:175], v[190:193], v[54:57]
	v_mfma_f32_16x16x32_bf16 v[50:53], v[180:183], v[190:193], v[50:53]
	v_mfma_f32_16x16x32_bf16 v[38:41], v[172:175], v[198:201], v[38:41]
	v_mfma_f32_16x16x32_bf16 v[34:37], v[180:183], v[198:201], v[34:37]
	v_mfma_f32_16x16x32_bf16 v[22:25], v[172:175], v[208:211], v[22:25]
	v_mfma_f32_16x16x32_bf16 v[18:21], v[180:183], v[208:211], v[18:21]
	v_mfma_f32_16x16x32_bf16 v[6:9], v[172:175], v[216:219], v[6:9]
	v_mfma_f32_16x16x32_bf16 v[2:5], v[180:183], v[216:219], v[2:5]
	s_setprio 0
	s_barrier
	s_add_i32 s41, 0, 0x18000
	s_add_i32 s51, 0, 0x1c000
	v_add_u32_e32 v164, s41, v157
	v_add_u32_e32 v180, s51, v157
	ds_read_b128 v[146:149], v164
	ds_read_b128 v[150:153], v164 offset:1024
	ds_read_b128 v[160:163], v164 offset:2048
	ds_read_b128 v[164:167], v164 offset:3072
	ds_read_b128 v[168:171], v180
	ds_read_b128 v[172:175], v180 offset:1024
	ds_read_b128 v[176:179], v180 offset:2048
	ds_read_b128 v[180:183], v180 offset:3072
	s_add_u32 s58, s58, 0x80000
	s_addc_u32 s59, s59, 0
	s_mov_b32 m0, s25
	v_lshl_add_u64 v[226:227], s[58:59], 0, v[134:135]
	ds_read_b128 v[186:189], v159 offset:32768
	ds_read_b128 v[190:193], v159 offset:33792
	ds_read_b128 v[194:197], v159 offset:34816
	ds_read_b128 v[198:201], v159 offset:35840
	ds_read_b128 v[202:205], v159 offset:36864
	ds_read_b128 v[208:211], v159 offset:37888
	ds_read_b128 v[212:215], v159 offset:38912
	ds_read_b128 v[216:219], v159 offset:39936
	global_load_lds_dwordx4 v[226:227], off
	v_lshl_add_u64 v[226:227], s[58:59], 0, v[136:137]
	s_mov_b32 m0, s30
	s_nop 0
	global_load_lds_dwordx4 v[226:227], off
	s_waitcnt vmcnt(8)
	s_waitcnt lgkmcnt(0)
	s_barrier
	s_setprio 1
	s_waitcnt lgkmcnt(0)
	v_mfma_f32_16x16x32_bf16 v[130:133], v[146:149], v[186:189], v[130:133]
	v_mfma_f32_16x16x32_bf16 v[126:129], v[160:163], v[186:189], v[126:129]
	v_mfma_f32_16x16x32_bf16 v[114:117], v[146:149], v[194:197], v[114:117]
	v_mfma_f32_16x16x32_bf16 v[110:113], v[160:163], v[194:197], v[110:113]
	v_mfma_f32_16x16x32_bf16 v[94:97], v[146:149], v[202:205], v[94:97]
	v_mfma_f32_16x16x32_bf16 v[90:93], v[160:163], v[202:205], v[90:93]
	v_mfma_f32_16x16x32_bf16 v[78:81], v[146:149], v[212:215], v[78:81]
	v_mfma_f32_16x16x32_bf16 v[74:77], v[160:163], v[212:215], v[74:77]
	v_mfma_f32_16x16x32_bf16 v[130:133], v[150:153], v[190:193], v[130:133]
	v_mfma_f32_16x16x32_bf16 v[126:129], v[164:167], v[190:193], v[126:129]
	v_mfma_f32_16x16x32_bf16 v[114:117], v[150:153], v[198:201], v[114:117]
	v_mfma_f32_16x16x32_bf16 v[110:113], v[164:167], v[198:201], v[110:113]
	v_mfma_f32_16x16x32_bf16 v[94:97], v[150:153], v[208:211], v[94:97]
	v_mfma_f32_16x16x32_bf16 v[90:93], v[164:167], v[208:211], v[90:93]
	v_mfma_f32_16x16x32_bf16 v[78:81], v[150:153], v[216:219], v[78:81]
	v_mfma_f32_16x16x32_bf16 v[74:77], v[164:167], v[216:219], v[74:77]
	s_setprio 0
	s_setprio 1
	v_mfma_f32_16x16x32_bf16 v[122:125], v[168:171], v[186:189], v[122:125]
	v_mfma_f32_16x16x32_bf16 v[118:121], v[176:179], v[186:189], v[118:121]
	v_mfma_f32_16x16x32_bf16 v[106:109], v[168:171], v[194:197], v[106:109]
	v_mfma_f32_16x16x32_bf16 v[102:105], v[176:179], v[194:197], v[102:105]
	v_mfma_f32_16x16x32_bf16 v[86:89], v[168:171], v[202:205], v[86:89]
	v_mfma_f32_16x16x32_bf16 v[82:85], v[176:179], v[202:205], v[82:85]
	v_mfma_f32_16x16x32_bf16 v[70:73], v[168:171], v[212:215], v[70:73]
	v_mfma_f32_16x16x32_bf16 v[66:69], v[176:179], v[212:215], v[66:69]
	v_mfma_f32_16x16x32_bf16 v[122:125], v[172:175], v[190:193], v[122:125]
	v_mfma_f32_16x16x32_bf16 v[118:121], v[180:183], v[190:193], v[118:121]
	v_mfma_f32_16x16x32_bf16 v[106:109], v[172:175], v[198:201], v[106:109]
	v_mfma_f32_16x16x32_bf16 v[102:105], v[180:183], v[198:201], v[102:105]
	v_mfma_f32_16x16x32_bf16 v[86:89], v[172:175], v[208:211], v[86:89]
	v_mfma_f32_16x16x32_bf16 v[82:85], v[180:183], v[208:211], v[82:85]
	v_mfma_f32_16x16x32_bf16 v[70:73], v[172:175], v[216:219], v[70:73]
	v_mfma_f32_16x16x32_bf16 v[66:69], v[180:183], v[216:219], v[66:69]
	s_setprio 0
	s_barrier
; #define PG8_STAGE(bufoff, gbase, voff) do { _Pragma("unroll") for (int _i = 0; _i < 2; ++_i) \
;         __builtin_amdgcn_global_load_lds((const unsigned*)((const char*)(gbase) + (voff)[_i]), (PG8_LAS unsigned*)(lds + (bufoff) + ldsw + _i * 8192), 16, 0, 0); } while (0)
; #define PG8_LDA(dst, b, h) do { _Pragma("unroll") for (int m = 0; m < 4; ++m) _Pragma("unroll") for (int k = 0; k < 2; ++k) dst[m][k] = *(const PG8_LAS bf16x8*)(lds + PG8_SA(b, h) + aoff + m * 2048 + k * 1024); } while (0)
; #define PG8_MMA(ai, bj, At, Bt) do { __builtin_amdgcn_s_setprio(1); _Pragma("unroll") for (int m = 0; m < 4; ++m) _Pragma("unroll") for (int n = 0; n < 2; ++n) _Pragma("unroll") for (int k = 0; k < 2; ++k) \
;         acc[ai][bj][m][n] = __builtin_amdgcn_mfma_f32_16x16x32_bf16(Bt[n][k], At[m][k], acc[ai][bj][m][n], 0, 0, 0); __builtin_amdgcn_s_setprio(0); } while (0)
; #define PG8_WAIT_V(n) asm volatile("s_waitcnt vmcnt(" #n ")" ::: "memory")
; #define PG8_WAIT_L(n) asm volatile("s_waitcnt lgkmcnt(" #n ")" ::: "memory")
; #define PG8_BAR __builtin_amdgcn_s_barrier()
; #define PG8_SCHED __builtin_amdgcn_sched_barrier(0)
; template <class Epi, class Sched, bool ALIGN_EPI = false, bool SP2 = false>
; __device__ __forceinline__ void gemm_phase(PG8_LAS unsigned char* lds, const Gemm g, const Sched& S, const Epi& E) {
;     ...
;         for (int t = 0; t < nt; t += 2) {
;             const bool last = (t == nt - 2);
;             const char* a1 = cA + (size_t)(t + 1) * kstep;
;             const char* a2 = last ? nA : cA + (size_t)(t + 2) * kstep; const char* b2 = last ? nB : cB + (size_t)(t + 2) * kstep;
;             const char* a3 = a2 + kstep; const char* b3 = b2 + kstep;
;     ...
;             PG8_LDA(At, 1, 1); PG8_STAGE(PG8_SB(1, 0), b3, voffB); PG8_STAGE(PG8_SB(1, 1), b3 + hstep, voffB); PG8_STAGE(PG8_SA(1, 0), a3, voffA);
;             PG8_WAIT_V(8); PG8_WAIT_L(0); PG8_BAR; PG8_MMA(1, 0, At, B0); PG8_MMA(1, 1, At, B1); PG8_BAR; PG8_SCHED;
	s_add_i32 s41, s41, s10
	v_lshl_add_u64 v[154:155], v[154:155], 0, s[22:23]
	s_mov_b32 m0, s41
	ds_read_b128 v[186:189], v159 offset:49152
	ds_read_b128 v[190:193], v159 offset:50176
	ds_read_b128 v[194:197], v159 offset:51200
	ds_read_b128 v[198:201], v159 offset:52224
	ds_read_b128 v[202:205], v159 offset:53248
	ds_read_b128 v[208:211], v159 offset:54272
	ds_read_b128 v[212:215], v159 offset:55296
	ds_read_b128 v[216:219], v159 offset:56320
	global_load_lds_dwordx4 v[154:155], off
	s_add_i32 m0, s41, 0x2000
	s_add_u32 s42, s42, 0x80080
	v_lshl_add_u64 v[154:155], v[220:221], 0, s[22:23]
	s_addc_u32 s43, s43, 0
	s_add_i32 s41, s51, s10
	global_load_lds_dwordx4 v[154:155], off
	v_lshl_add_u64 v[154:155], s[42:43], 0, v[0:1]
	s_mov_b32 m0, s41
	s_nop 0
	global_load_lds_dwordx4 v[154:155], off
	v_lshl_add_u64 v[154:155], s[42:43], 0, v[138:139]
	s_add_i32 m0, s41, 0x2000
	s_nop 0
	global_load_lds_dwordx4 v[154:155], off
	v_lshl_add_u64 v[154:155], v[222:223], 0, s[22:23]
	s_mov_b32 m0, s9
	s_nop 0
	global_load_lds_dwordx4 v[154:155], off
	v_lshl_add_u64 v[154:155], v[224:225], 0, s[22:23]
	s_mov_b32 m0, s15
	s_nop 0
	global_load_lds_dwordx4 v[154:155], off
	s_waitcnt vmcnt(8)
	s_waitcnt lgkmcnt(0)
	s_barrier
	s_setprio 1
	s_waitcnt lgkmcnt(0)
	v_mfma_f32_16x16x32_bf16 v[62:65], v[146:149], v[186:189], v[62:65]
	v_mfma_f32_16x16x32_bf16 v[58:61], v[160:163], v[186:189], v[58:61]
	v_mfma_f32_16x16x32_bf16 v[46:49], v[146:149], v[194:197], v[46:49]
	v_mfma_f32_16x16x32_bf16 v[42:45], v[160:163], v[194:197], v[42:45]
	v_mfma_f32_16x16x32_bf16 v[30:33], v[146:149], v[202:205], v[30:33]
	v_mfma_f32_16x16x32_bf16 v[26:29], v[160:163], v[202:205], v[26:29]
	v_mfma_f32_16x16x32_bf16 v[14:17], v[146:149], v[212:215], v[14:17]
	v_mfma_f32_16x16x32_bf16 v[10:13], v[160:163], v[212:215], v[10:13]
	v_mfma_f32_16x16x32_bf16 v[62:65], v[150:153], v[190:193], v[62:65]
	v_mfma_f32_16x16x32_bf16 v[58:61], v[164:167], v[190:193], v[58:61]
	v_mfma_f32_16x16x32_bf16 v[46:49], v[150:153], v[198:201], v[46:49]
	v_mfma_f32_16x16x32_bf16 v[42:45], v[164:167], v[198:201], v[42:45]
	v_mfma_f32_16x16x32_bf16 v[30:33], v[150:153], v[208:211], v[30:33]
	v_mfma_f32_16x16x32_bf16 v[26:29], v[164:167], v[208:211], v[26:29]
	v_mfma_f32_16x16x32_bf16 v[14:17], v[150:153], v[216:219], v[14:17]
	v_mfma_f32_16x16x32_bf16 v[10:13], v[164:167], v[216:219], v[10:13]
	s_setprio 0
	s_setprio 1
	v_mfma_f32_16x16x32_bf16 v[54:57], v[168:171], v[186:189], v[54:57]
	v_mfma_f32_16x16x32_bf16 v[50:53], v[176:179], v[186:189], v[50:53]
	v_mfma_f32_16x16x32_bf16 v[38:41], v[168:171], v[194:197], v[38:41]
	v_mfma_f32_16x16x32_bf16 v[34:37], v[176:179], v[194:197], v[34:37]
	v_mfma_f32_16x16x32_bf16 v[22:25], v[168:171], v[202:205], v[22:25]
	v_mfma_f32_16x16x32_bf16 v[18:21], v[176:179], v[202:205], v[18:21]
	v_mfma_f32_16x16x32_bf16 v[6:9], v[168:171], v[212:215], v[6:9]
	v_mfma_f32_16x16x32_bf16 v[2:5], v[176:179], v[212:215], v[2:5]
	v_mfma_f32_16x16x32_bf16 v[54:57], v[172:175], v[190:193], v[54:57]
	v_mfma_f32_16x16x32_bf16 v[50:53], v[180:183], v[190:193], v[50:53]
	v_mfma_f32_16x16x32_bf16 v[38:41], v[172:175], v[198:201], v[38:41]
	v_mfma_f32_16x16x32_bf16 v[34:37], v[180:183], v[198:201], v[34:37]
	v_mfma_f32_16x16x32_bf16 v[22:25], v[172:175], v[208:211], v[22:25]
	v_mfma_f32_16x16x32_bf16 v[18:21], v[180:183], v[208:211], v[18:21]
	v_mfma_f32_16x16x32_bf16 v[6:9], v[172:175], v[216:219], v[6:9]
	v_mfma_f32_16x16x32_bf16 v[2:5], v[180:183], v[216:219], v[2:5]
	s_add_i32 s19, s19, 2
	s_add_u32 s14, s14, 0x100
	s_addc_u32 s18, s18, 0
	s_add_u32 s0, s0, 0x100
	s_addc_u32 s1, s1, 0
	s_add_u32 s41, s0, 0xfff80080
	s_addc_u32 s42, s1, -1
	s_add_i32 s51, 0, 0x10000
	s_cmp_eq_u32 s19, 28
	s_cselect_b32 s59, s2, s42
	s_cselect_b32 s58, s3, s41
	v_add_u32_e32 v154, s51, v157
	s_cselect_b32 s43, s8, s18
	s_cselect_b32 s42, s12, s14
	s_cmp_gt_u32 s19, 29
	s_setprio 0
	s_barrier
	s_cbranch_scc0 .Lmy_rot1
	s_and_b64 vcc, exec, s[48:49]
	s_cbranch_vccz .LBB0_1275
	s_barrier
